# static s_setprio 1 for waves 4-7 during the prompt attention units (strategy: one static priority raise for the younger half)
# baseline (speedup 1.0000x reference)
.LBB0_1901:
	s_or_b64 exec, exec, s[0:1]
	s_and_b32 s34, s68, 7
	s_ashr_i32 s76, s4, 6
	s_cmp_ge_u32 s76, 4
	s_cbranch_scc0 .Lprio_skip1
	s_setprio 1
.Lprio_skip1:
	s_lshl_b64 s[24:25], s[22:23], 13
	s_ashr_i32 s0, s71, 31
	s_add_u32 s1, s24, s71
	s_addc_u32 s0, s25, s0
	s_lshl_b32 s8, s76, 5
	s_ashr_i32 s6, s8, 31
	s_add_u32 s30, s1, s8
	s_addc_u32 s31, s0, s6
	s_lshl_b64 s[0:1], s[30:31], 10
	s_add_u32 s0, s96, s0
	s_addc_u32 s1, s97, s1
	s_lshl_b32 s35, s34, 7
	s_add_u32 s6, s0, s35
	s_addc_u32 s7, s1, 0
	s_lshl_b64 s[0:1], s[22:23], 23
	v_readlane_b32 s2, v254, 23
	v_readlane_b32 s3, v254, 24
	s_add_u32 s23, s2, s0
	s_addc_u32 s27, s3, s1
	s_add_u32 s26, s23, s35
	s_addc_u32 s27, s27, 0
	s_lshl_b32 s28, s76, 3
	v_and_b32_e32 v202, 63, v38
	s_ashr_i32 s29, s28, 31
	v_readlane_b32 s2, v254, 25
	v_lshlrev_b32_e32 v2, 10, v202
	v_readlane_b32 s3, v254, 26
	s_add_u32 s0, s2, s0
	v_lshl_add_u64 v[4:5], s[26:27], 0, v[2:3]
	s_addc_u32 s1, s3, s1
	v_lshl_add_u64 v[186:187], s[28:29], 1, v[4:5]
	v_bfe_u32 v220, v38, 2, 6
	v_bfe_u32 v221, v38, 4, 2
	v_and_b32_e32 v222, 3, v38
	v_xor_b32_e32 v221, v221, v222
	v_bfe_u32 v222, v38, 8, 1
	v_lshl_add_u32 v221, v222, 2, v221
	v_lshlrev_b32_e32 v221, 4, v221
	v_lshl_add_u32 v220, v220, 10, v221
	v_mov_b32_e32 v221, 0
	v_lshl_add_u64 v[186:187], s[26:27], 0, v[220:221]
	s_add_u32 s28, s0, s35
	s_addc_u32 s29, s1, 0
	s_lshl_b32 s0, s76, 4
	v_bfe_u32 v2, v38, 2, 4
	v_and_or_b32 v2, s0, 48, v2
	s_ashr_i32 s0, s4, 3
	v_lshlrev_b32_e32 v2, 10, v2
	s_andn2_b32 s0, s0, 31
	v_lshl_add_u64 v[4:5], s[28:29], 0, v[2:3]
	s_ashr_i32 s1, s0, 31
	v_lshl_add_u64 v[4:5], s[0:1], 1, v[4:5]
	s_lshl_b32 s0, s76, 10
	v_lshlrev_b32_e32 v203, 3, v38
	s_cmp_lg_u32 16, -1
	s_waitcnt vmcnt(0) lgkmcnt(0)
	v_and_b32_e32 v39, 24, v203
	s_cselect_b32 s1, 16, 0
	v_bfe_u32 v194, v38, 5, 1
	v_lshlrev_b32_e32 v2, 1, v39
	s_add_i32 s77, s0, s1
	s_mov_b32 s1, m0
	s_mov_b32 m0, s77
	s_nop 0
	global_load_lds_dwordx4 v[186:187], off
	s_mov_b32 m0, s1
	v_and_b32_e32 v204, 31, v38
	v_lshl_add_u64 v[36:37], v[4:5], 0, v[2:3]
	s_add_i32 s78, s77, 0x6000
	s_mov_b32 s1, m0
	s_mov_b32 m0, s78
	s_nop 0
	global_load_lds_dwordx4 v[36:37], off
	s_mov_b32 m0, s1
	v_lshlrev_b32_e32 v195, 4, v194
	v_lshl_add_u64 v[4:5], v[186:187], 0, s[10:11]
	s_add_i32 s1, s77, 0x2000
	s_mov_b32 s23, m0
	s_mov_b32 m0, s1
	s_nop 0
	global_load_lds_dwordx4 v[4:5], off
	s_mov_b32 m0, s23
	v_lshl_or_b32 v2, v204, 10, v195
	global_load_dwordx4 v[126:129], v2, s[6:7]
	global_load_dwordx4 v[122:125], v2, s[6:7] offset:32
	global_load_dwordx4 v[118:121], v2, s[6:7] offset:64
	global_load_dwordx4 v[114:117], v2, s[6:7] offset:96
	v_lshlrev_b32_e32 v2, 10, v194
	v_lshlrev_b32_e32 v4, 4, v204
	v_add3_u32 v210, 16, v2, v4
	v_bfe_u32 v222, v204, 2, 2
	v_and_b32_e32 v223, 1, v222
	v_xor_b32_e32 v223, v223, v194
	v_and_b32_e32 v222, 2, v222
	v_or_b32_e32 v222, v222, v223
	v_lshlrev_b32_e32 v222, 4, v222
	v_lshl_add_u32 v210, v204, 6, v222
	v_xor_b32_e32 v224, 32, v210
	v_add_u32_e32 v210, 16, v210
	v_add_u32_e32 v224, 16, v224
	v_lshl_add_u64 v[4:5], v[186:187], 0, s[12:13]
	s_add_i32 s1, s77, 0x4000
	s_mov_b32 s6, m0
	s_mov_b32 m0, s1
	s_nop 0
	global_load_lds_dwordx4 v[4:5], off
	s_mov_b32 m0, s6
	v_add_u32_e32 v2, 16, v195
	s_waitcnt vmcnt(3) lgkmcnt(0)
	s_barrier
	v_add_u32_e32 v2, 0x14800, v2
	ds_read_b128 v[20:23], v210
	ds_read_b128 v[4:7], v2
	ds_read_b128 v[8:11], v2 offset:32
	ds_read_b128 v[12:15], v2 offset:64
	ds_read_b128 v[16:19], v2 offset:96
	ds_read_b128 v[42:45], v210 offset:2048
	v_or_b32_e32 v209, s8, v204
	s_cmp_eq_u32 s5, 0
	v_lshlrev_b32_e32 v205, 2, v194
	s_waitcnt vmcnt(3) lgkmcnt(1)
	v_mfma_f32_32x32x16_bf16 v[4:19], v[20:23], v[126:129], v[4:19]
	ds_read_b128 v[20:23], v2 offset:128
	ds_read_b128 v[24:27], v2 offset:160
	ds_read_b128 v[28:31], v2 offset:192
	ds_read_b128 v[32:35], v2 offset:224
	s_waitcnt lgkmcnt(0)
	v_mfma_f32_32x32x16_bf16 v[20:35], v[42:45], v[126:129], v[20:35]
	ds_read_b128 v[42:45], v224
	ds_read_b128 v[46:49], v224 offset:2048
	s_waitcnt vmcnt(2) lgkmcnt(1)
	v_mfma_f32_32x32x16_bf16 v[4:19], v[42:45], v[122:125], v[4:19]
	s_waitcnt lgkmcnt(0)
	v_mfma_f32_32x32x16_bf16 v[20:35], v[46:49], v[122:125], v[20:35]
	ds_read_b128 v[42:45], v210 offset:4096
	ds_read_b128 v[46:49], v210 offset:6144
	s_waitcnt vmcnt(1) lgkmcnt(1)
	v_mfma_f32_32x32x16_bf16 v[4:19], v[42:45], v[118:121], v[4:19]
	s_waitcnt lgkmcnt(0)
	v_mfma_f32_32x32x16_bf16 v[20:35], v[46:49], v[118:121], v[20:35]
	ds_read_b128 v[42:45], v224 offset:4096
	ds_read_b128 v[46:49], v224 offset:6144
	s_waitcnt vmcnt(0) lgkmcnt(1)
	v_mfma_f32_32x32x16_bf16 v[4:19], v[42:45], v[114:117], v[4:19]
	s_waitcnt lgkmcnt(0)
	v_mfma_f32_32x32x16_bf16 v[20:35], v[46:49], v[114:117], v[20:35]
	s_cbranch_scc0 .LBB0_1903
	v_lshlrev_b32_e32 v2, 2, v194
	v_or_b32_e32 v41, 32, v2
	v_cmp_le_i32_e32 vcc, v41, v209
	v_or_b32_e32 v41, 33, v2
	s_nop 6
	v_cndmask_b32_e32 v20, v199, v20, vcc
	v_cmp_lt_i32_e32 vcc, v2, v209
	s_nop 1
	v_cndmask_b32_e32 v5, v199, v5, vcc
	v_cmp_le_i32_e32 vcc, v2, v209
	s_nop 1
	v_cndmask_b32_e32 v4, v199, v4, vcc
	v_cmp_le_i32_e32 vcc, v41, v209
	v_or_b32_e32 v41, 2, v2
	s_nop 0
	v_cndmask_b32_e32 v21, v199, v21, vcc
	v_cmp_le_i32_e32 vcc, v41, v209
	v_or_b32_e32 v41, 34, v2
	s_nop 0
	v_cndmask_b32_e32 v6, v199, v6, vcc
	v_cmp_le_i32_e32 vcc, v41, v209
	v_or_b32_e32 v41, 3, v2
	s_nop 0
	v_cndmask_b32_e32 v22, v199, v22, vcc
	v_cmp_le_i32_e32 vcc, v41, v209
	v_or_b32_e32 v41, 35, v2
	s_nop 0
	v_cndmask_b32_e32 v7, v199, v7, vcc
	v_cmp_le_i32_e32 vcc, v41, v209
	v_or_b32_e32 v41, 8, v2
	s_nop 0
	v_cndmask_b32_e32 v23, v199, v23, vcc
	v_cmp_le_i32_e32 vcc, v41, v209
	v_or_b32_e32 v41, 40, v2
	s_nop 0
	v_cndmask_b32_e32 v8, v199, v8, vcc
	v_cmp_le_i32_e32 vcc, v41, v209
	v_or_b32_e32 v41, 9, v2
	s_nop 0
	v_cndmask_b32_e32 v24, v199, v24, vcc
	v_cmp_le_i32_e32 vcc, v41, v209
	v_or_b32_e32 v41, 41, v2
	s_nop 0
	v_cndmask_b32_e32 v9, v199, v9, vcc
	v_cmp_le_i32_e32 vcc, v41, v209
	v_or_b32_e32 v41, 10, v2
	s_nop 0
	v_cndmask_b32_e32 v25, v199, v25, vcc
	v_cmp_le_i32_e32 vcc, v41, v209
	v_or_b32_e32 v41, 42, v2
	s_nop 0
	v_cndmask_b32_e32 v10, v199, v10, vcc
	v_cmp_le_i32_e32 vcc, v41, v209
	v_or_b32_e32 v41, 11, v2
	s_nop 0
	v_cndmask_b32_e32 v26, v199, v26, vcc
	v_cmp_le_i32_e32 vcc, v41, v209
	v_or_b32_e32 v41, 43, v2
	s_nop 0
	v_cndmask_b32_e32 v11, v199, v11, vcc
	v_cmp_le_i32_e32 vcc, v41, v209
	v_or_b32_e32 v41, 16, v2
	s_nop 0
	v_cndmask_b32_e32 v27, v199, v27, vcc
	v_cmp_le_i32_e32 vcc, v41, v209
	v_or_b32_e32 v41, 48, v2
	s_nop 0
	v_cndmask_b32_e32 v12, v199, v12, vcc
	v_cmp_le_i32_e32 vcc, v41, v209
	v_or_b32_e32 v41, 17, v2
	s_nop 0
	v_cndmask_b32_e32 v28, v199, v28, vcc
	v_cmp_le_i32_e32 vcc, v41, v209
	v_or_b32_e32 v41, 49, v2
	s_nop 0
	v_cndmask_b32_e32 v13, v199, v13, vcc
	v_cmp_le_i32_e32 vcc, v41, v209
	v_or_b32_e32 v41, 18, v2
	s_nop 0
	v_cndmask_b32_e32 v29, v199, v29, vcc
	v_cmp_le_i32_e32 vcc, v41, v209
	v_or_b32_e32 v41, 50, v2
	s_nop 0
	v_cndmask_b32_e32 v14, v199, v14, vcc
	v_cmp_le_i32_e32 vcc, v41, v209
	v_or_b32_e32 v41, 19, v2
	s_nop 0
	v_cndmask_b32_e32 v30, v199, v30, vcc
	v_cmp_le_i32_e32 vcc, v41, v209
	v_or_b32_e32 v41, 51, v2
	s_nop 0
	v_cndmask_b32_e32 v15, v199, v15, vcc
	v_cmp_le_i32_e32 vcc, v41, v209
	v_or_b32_e32 v41, 24, v2
	s_nop 0
	v_cndmask_b32_e32 v31, v199, v31, vcc
	v_cmp_le_i32_e32 vcc, v41, v209
	v_or_b32_e32 v41, 56, v2
	s_nop 0
	v_cndmask_b32_e32 v16, v199, v16, vcc
	v_cmp_le_i32_e32 vcc, v41, v209
	v_or_b32_e32 v41, 25, v2
	s_nop 0
	v_cndmask_b32_e32 v32, v199, v32, vcc
	v_cmp_le_i32_e32 vcc, v41, v209
	v_or_b32_e32 v41, 57, v2
	s_nop 0
	v_cndmask_b32_e32 v17, v199, v17, vcc
	v_cmp_le_i32_e32 vcc, v41, v209
	v_or_b32_e32 v41, 26, v2
	s_nop 0
	v_cndmask_b32_e32 v33, v199, v33, vcc
	v_cmp_le_i32_e32 vcc, v41, v209
	v_or_b32_e32 v41, 58, v2
	s_nop 0
	v_cndmask_b32_e32 v18, v199, v18, vcc
	v_cmp_le_i32_e32 vcc, v41, v209
	v_or_b32_e32 v41, 27, v2
	v_or_b32_e32 v2, 59, v2
	v_cndmask_b32_e32 v34, v199, v34, vcc
	v_cmp_le_i32_e32 vcc, v41, v209
	s_nop 1
	v_cndmask_b32_e32 v19, v199, v19, vcc
	v_cmp_le_i32_e32 vcc, v2, v209
	s_nop 1
	v_cndmask_b32_e32 v35, v199, v35, vcc

.LBB0_1977:
	v_add_u32_e32 v82, s80, v206
	ds_read_b64_tr_b16 v[10:11], v82 offset:24576
	ds_read_b64_tr_b16 v[12:13], v82 offset:25088
	v_cvt_pk_bf16_f32 v6, v66, v67
	v_cvt_pk_bf16_f32 v7, v68, v69
	v_cvt_pk_bf16_f32 v8, v70, v71
	v_cvt_pk_bf16_f32 v9, v72, v73
	ds_read_b64_tr_b16 v[14:15], v82 offset:25600
	ds_read_b64_tr_b16 v[16:17], v82 offset:26112
	s_waitcnt lgkmcnt(2)
	v_mfma_f32_32x32x16_bf16 v[34:49], v[6:9], v[10:13], v[34:49]
	ds_read_b64_tr_b16 v[10:11], v82 offset:28672
	ds_read_b64_tr_b16 v[12:13], v82 offset:29184
	v_add_f32_e32 v5, v66, v67
	v_add_f32_e32 v5, v68, v5
	v_add_f32_e32 v5, v69, v5
	v_add_f32_e32 v5, v70, v5
	ds_read_b64_tr_b16 v[66:67], v82 offset:29696
	ds_read_b64_tr_b16 v[68:69], v82 offset:30208
	v_add_f32_e32 v5, v71, v5
	s_waitcnt lgkmcnt(2)
	v_mfma_f32_32x32x16_bf16 v[18:33], v[6:9], v[10:13], v[18:33]
	v_add_f32_e32 v5, v72, v5
	v_cvt_pk_bf16_f32 v6, v74, v75
	v_cvt_pk_bf16_f32 v7, v76, v77
	v_cvt_pk_bf16_f32 v8, v78, v79
	v_cvt_pk_bf16_f32 v9, v80, v81
	v_add_f32_e32 v5, v73, v5
	v_add_f32_e32 v5, v74, v5
	v_mfma_f32_32x32x16_bf16 v[34:49], v[6:9], v[14:17], v[34:49]
	v_add_f32_e32 v5, v75, v5
	v_add_f32_e32 v5, v76, v5
	v_add_f32_e32 v5, v77, v5
	v_add_f32_e32 v5, v78, v5
	v_add_f32_e32 v5, v79, v5
	v_add_f32_e32 v5, v80, v5
	v_cvt_pk_bf16_f32 v10, v50, v51
	s_waitcnt lgkmcnt(0)
	v_mfma_f32_32x32x16_bf16 v[18:33], v[6:9], v[66:69], v[18:33]
	ds_read_b64_tr_b16 v[6:7], v82 offset:26624
	ds_read_b64_tr_b16 v[8:9], v82 offset:27136
	v_cvt_pk_bf16_f32 v11, v52, v53
	v_cvt_pk_bf16_f32 v12, v54, v55
	v_cvt_pk_bf16_f32 v13, v56, v57
	ds_read_b64_tr_b16 v[14:15], v82 offset:27648
	ds_read_b64_tr_b16 v[16:17], v82 offset:28160
	v_add_f32_e32 v5, v81, v5
	v_add_f32_e32 v5, v50, v5
	s_waitcnt lgkmcnt(2)
	v_mfma_f32_32x32x16_bf16 v[34:49], v[10:13], v[6:9], v[34:49]
	ds_read_b64_tr_b16 v[6:7], v82 offset:30720
	ds_read_b64_tr_b16 v[8:9], v82 offset:31232
	v_add_f32_e32 v5, v51, v5
	v_add_f32_e32 v5, v52, v5
	v_add_f32_e32 v5, v53, v5
	v_add_f32_e32 v5, v54, v5
	v_add_f32_e32 v5, v55, v5
	v_add_f32_e32 v5, v56, v5
	s_waitcnt lgkmcnt(0)
	v_mfma_f32_32x32x16_bf16 v[18:33], v[10:13], v[6:9], v[18:33]
	ds_read_b64_tr_b16 v[50:51], v82 offset:31744
	ds_read_b64_tr_b16 v[52:53], v82 offset:32256
	v_add_f32_e32 v5, v57, v5
	v_add_f32_e32 v5, v58, v5
	v_add_f32_e32 v5, v59, v5
	v_add_f32_e32 v5, v60, v5
	v_cvt_pk_bf16_f32 v6, v58, v59
	v_cvt_pk_bf16_f32 v7, v60, v61
	v_cvt_pk_bf16_f32 v8, v62, v63
	v_cvt_pk_bf16_f32 v9, v64, v65
	v_add_f32_e32 v5, v61, v5
	v_mfma_f32_32x32x16_bf16 v[34:49], v[6:9], v[14:17], v[34:49]
	v_add_f32_e32 v5, v62, v5
	v_add_f32_e32 v5, v63, v5
	v_add_f32_e32 v5, v64, v5
	v_add_f32_e32 v5, v65, v5
	v_add_f32_e32 v2, v2, v5
	v_mov_b32_e32 v5, v2
	s_nop 1
	v_permlane32_swap_b32_e32 v2, v5
	s_waitcnt lgkmcnt(0)
	v_mfma_f32_32x32x16_bf16 v[18:33], v[6:9], v[50:53], v[18:33]
	v_cmp_gt_u32_e32 vcc, 32, v202
	s_and_saveexec_b64 s[0:1], vcc
	v_add_f32_e32 v2, v2, v5
	ds_write_b32 v207, v2 offset:49280
	s_or_b64 exec, exec, s[0:1]
	s_waitcnt lgkmcnt(0)
	ds_read_b128 v[6:9], v4 offset:49280
	ds_read_b128 v[10:13], v4 offset:49312
	s_sub_i32 s0, 0x1f00, s71
	s_lshl_b64 s[4:5], s[30:31], 11
	s_add_u32 s1, s60, s4
	s_waitcnt lgkmcnt(1)
	v_rcp_f32_e32 v2, v6
	v_rcp_f32_e32 v5, v7
	v_rcp_f32_e32 v14, v8
	v_rcp_f32_e32 v15, v9
	s_waitcnt lgkmcnt(0)
	v_rcp_f32_e32 v16, v10
	ds_read_b128 v[6:9], v4 offset:49344
	v_rcp_f32_e32 v17, v11
	v_rcp_f32_e32 v50, v12
	v_rcp_f32_e32 v51, v13
	ds_read_b128 v[10:13], v4 offset:49376
	s_addc_u32 s5, s61, s5
	s_lshl_b32 s4, s76, 12
	s_add_i32 s6, s4, 16
	s_waitcnt lgkmcnt(1)
	v_rcp_f32_e32 v4, v6
	v_rcp_f32_e32 v6, v7
	v_rcp_f32_e32 v7, v8
	v_rcp_f32_e32 v8, v9
	s_waitcnt lgkmcnt(0)
	v_rcp_f32_e32 v9, v10
	v_rcp_f32_e32 v10, v11
	v_rcp_f32_e32 v11, v12
	v_rcp_f32_e32 v12, v13
	v_lshl_add_u32 v13, v204, 1, s6
	v_lshlrev_b32_e32 v52, 7, v205
	v_mul_f32_e32 v34, v34, v2
	v_mul_f32_e32 v2, v18, v2
	v_add_u32_e32 v53, v13, v52
	v_cvt_pk_bf16_f32 v2, v2, v3
	ds_write_b16 v53, v2 offset:51264
	v_mul_f32_e32 v2, v35, v5
	v_cvt_pk_bf16_f32 v2, v2, v3
	ds_write_b16 v53, v2 offset:51328
	v_mul_f32_e32 v2, v19, v5
	v_cvt_pk_bf16_f32 v2, v2, v3
	ds_write_b16 v53, v2 offset:51392
	v_mul_f32_e32 v2, v36, v14
	v_cvt_pk_bf16_f32 v2, v2, v3
	ds_write_b16 v53, v2 offset:51456
	v_mul_f32_e32 v2, v20, v14
	v_cvt_pk_bf16_f32 v2, v2, v3
	ds_write_b16 v53, v2 offset:51520
	v_mul_f32_e32 v2, v37, v15
	v_cvt_pk_bf16_f32 v2, v2, v3
	ds_write_b16 v53, v2 offset:51584
	v_mul_f32_e32 v2, v21, v15
	v_cvt_pk_bf16_f32 v2, v2, v3
	ds_write_b16 v53, v2 offset:51648
	v_or_b32_e32 v2, 0x400, v52
	v_mul_f32_e32 v5, v38, v16
	v_add_u32_e32 v2, v13, v2
	v_cvt_pk_bf16_f32 v5, v5, v3
	v_cvt_pk_bf16_f32 v34, v34, v3
	ds_write_b16 v53, v34 offset:51200
	ds_write_b16 v2, v5 offset:51200
	v_mul_f32_e32 v5, v22, v16
	v_cvt_pk_bf16_f32 v5, v5, v3
	ds_write_b16 v2, v5 offset:51264
	v_or_b32_e32 v2, 0x480, v52
	v_mul_f32_e32 v5, v39, v17
	v_add_u32_e32 v2, v13, v2
	v_cvt_pk_bf16_f32 v5, v5, v3
	ds_write_b16 v2, v5 offset:51200
	v_mul_f32_e32 v5, v23, v17
	v_cvt_pk_bf16_f32 v5, v5, v3
	ds_write_b16 v2, v5 offset:51264
	v_or_b32_e32 v2, 0x500, v52
	v_mul_f32_e32 v5, v40, v50
	v_add_u32_e32 v2, v13, v2
	v_cvt_pk_bf16_f32 v5, v5, v3
	ds_write_b16 v2, v5 offset:51200
	v_mul_f32_e32 v5, v24, v50
	v_cvt_pk_bf16_f32 v5, v5, v3
	ds_write_b16 v2, v5 offset:51264
	v_or_b32_e32 v2, 0x580, v52
	v_mul_f32_e32 v5, v41, v51
	v_add_u32_e32 v2, v13, v2
	v_cvt_pk_bf16_f32 v5, v5, v3
	ds_write_b16 v2, v5 offset:51200
	v_mul_f32_e32 v5, v25, v51
	v_cvt_pk_bf16_f32 v5, v5, v3
	ds_write_b16 v2, v5 offset:51264
	v_or_b32_e32 v2, 0x800, v52
	v_mul_f32_e32 v5, v42, v4
	v_mul_f32_e32 v4, v26, v4
	v_add_u32_e32 v2, v13, v2
	v_cvt_pk_bf16_f32 v4, v4, v3
	v_cvt_pk_bf16_f32 v5, v5, v3
	ds_write_b16 v2, v5 offset:51200
	ds_write_b16 v2, v4 offset:51264
	v_or_b32_e32 v2, 0x880, v52
	v_mul_f32_e32 v4, v43, v6
	v_add_u32_e32 v2, v13, v2
	v_cvt_pk_bf16_f32 v4, v4, v3
	ds_write_b16 v2, v4 offset:51200
	v_mul_f32_e32 v4, v27, v6
	v_cvt_pk_bf16_f32 v4, v4, v3
	ds_write_b16 v2, v4 offset:51264
	v_or_b32_e32 v2, 0x900, v52
	v_mul_f32_e32 v4, v44, v7
	v_add_u32_e32 v2, v13, v2
	v_cvt_pk_bf16_f32 v4, v4, v3
	ds_write_b16 v2, v4 offset:51200
	v_mul_f32_e32 v4, v28, v7
	v_cvt_pk_bf16_f32 v4, v4, v3
	ds_write_b16 v2, v4 offset:51264
	v_or_b32_e32 v2, 0x980, v52
	v_mul_f32_e32 v4, v45, v8
	v_add_u32_e32 v2, v13, v2
	v_cvt_pk_bf16_f32 v4, v4, v3
	ds_write_b16 v2, v4 offset:51200
	v_mul_f32_e32 v4, v29, v8
	v_cvt_pk_bf16_f32 v4, v4, v3
	ds_write_b16 v2, v4 offset:51264
	v_or_b32_e32 v2, 0xc00, v52
	v_mul_f32_e32 v4, v46, v9
	v_add_u32_e32 v2, v13, v2
	v_cvt_pk_bf16_f32 v4, v4, v3
	ds_write_b16 v2, v4 offset:51200
	v_mul_f32_e32 v4, v30, v9
	v_cvt_pk_bf16_f32 v4, v4, v3
	ds_write_b16 v2, v4 offset:51264
	v_or_b32_e32 v2, 0xc80, v52
	v_mul_f32_e32 v4, v47, v10
	v_add_u32_e32 v2, v13, v2
	v_cvt_pk_bf16_f32 v4, v4, v3
	ds_write_b16 v2, v4 offset:51200
	v_mul_f32_e32 v4, v31, v10
	v_cvt_pk_bf16_f32 v4, v4, v3
	ds_write_b16 v2, v4 offset:51264
	v_or_b32_e32 v2, 0xd00, v52
	v_mul_f32_e32 v4, v48, v11
	v_add_u32_e32 v2, v13, v2
	v_cvt_pk_bf16_f32 v4, v4, v3
	ds_write_b16 v2, v4 offset:51200
	v_mul_f32_e32 v4, v32, v11
	v_cvt_pk_bf16_f32 v4, v4, v3
	ds_write_b16 v2, v4 offset:51264
	v_or_b32_e32 v2, 0xd80, v52
	v_mul_f32_e32 v4, v49, v12
	v_add_u32_e32 v2, v13, v2
	v_cvt_pk_bf16_f32 v4, v4, v3
	ds_write_b16 v2, v4 offset:51200
	v_mul_f32_e32 v4, v33, v12
	v_cvt_pk_bf16_f32 v4, v4, v3
	ds_write_b16 v2, v4 offset:51264
	s_lshl_b32 s34, s81, 1
	v_lshlrev_b32_e32 v2, 1, v203
	s_add_u32 s4, s1, s34
	v_and_b32_e32 v2, 0x70, v2
	s_addc_u32 s5, s5, 0
	v_lshrrev_b32_e32 v16, 3, v202
	v_add_u32_e32 v17, s6, v2
	s_waitcnt lgkmcnt(0)
	v_lshl_add_u64 v[12:13], s[4:5], 0, v[2:3]
	v_lshl_add_u32 v2, v16, 7, v17
	v_or_b32_e32 v18, 8, v16
	ds_read_b128 v[4:7], v2 offset:51200
	v_lshl_add_u32 v8, v18, 7, v17
	ds_read_b128 v[8:11], v8 offset:51200
	v_lshlrev_b32_e32 v2, 11, v16
	v_lshl_add_u64 v[14:15], v[12:13], 0, v[2:3]
	v_lshlrev_b32_e32 v2, 11, v18
	s_waitcnt lgkmcnt(1)
	global_store_dwordx4 v[14:15], v[4:7], off
	v_mov_b32_e32 v44, v0
	s_lshr_b32 s36, s70, 6
	v_lshl_add_u64 v[4:5], v[12:13], 0, v[2:3]
	v_or_b32_e32 v2, 16, v16
	s_waitcnt lgkmcnt(0)
	global_store_dwordx4 v[4:5], v[8:11], off
	v_lshl_add_u32 v4, v2, 7, v17
	v_or_b32_e32 v16, 24, v16
	ds_read_b128 v[4:7], v4 offset:51200
	v_lshl_add_u32 v8, v16, 7, v17
	ds_read_b128 v[8:11], v8 offset:51200
	v_lshlrev_b32_e32 v2, 11, v2
	v_lshl_add_u64 v[14:15], v[12:13], 0, v[2:3]
	v_lshlrev_b32_e32 v2, 11, v16
	s_waitcnt lgkmcnt(1)
	global_store_dwordx4 v[14:15], v[4:7], off
	s_mov_b32 s39, 1
	s_movk_i32 s7, 0x4000
	v_lshl_add_u64 v[4:5], v[12:13], 0, v[2:3]
	s_waitcnt lgkmcnt(0)
	global_store_dwordx4 v[4:5], v[8:11], off
	s_waitcnt lgkmcnt(0)
	s_barrier
	v_mov_b32_e32 v214, 0
	v_readfirstlane_b32 s6, v44
	s_ashr_i32 s35, s6, 6
	s_cmp_ge_u32 s35, 4
	s_cbranch_scc0 .Lprio_skip2
	s_setprio 1
.Lprio_skip2:
	s_add_u32 s0, s24, s0
	s_addc_u32 s1, s25, 0
	s_lshl_b32 s8, s35, 5
	s_ashr_i32 s4, s8, 31
	s_add_u32 s24, s0, s8
	s_addc_u32 s25, s1, s4
	s_lshl_b64 s[0:1], s[24:25], 10
	s_add_u32 s0, s96, s0
	s_addc_u32 s1, s97, s1
	s_add_u32 s0, s0, s34
	s_addc_u32 s1, s1, 0
	s_and_b32 s4, s6, 0x3fffffc0
	v_and_b32_e32 v204, 63, v44
	s_lshl_b32 s4, s4, 2
	s_add_i32 s30, s4, 16
	v_lshlrev_b32_e32 v2, 10, v204
	s_lshl_b32 s4, s35, 3
	v_lshl_add_u64 v[4:5], s[26:27], 0, v[2:3]
	s_ashr_i32 s5, s4, 31
	v_lshl_add_u64 v[196:197], s[4:5], 1, v[4:5]
	v_bfe_u32 v220, v44, 2, 6
	v_bfe_u32 v221, v44, 4, 2
	v_and_b32_e32 v222, 3, v44
	v_xor_b32_e32 v221, v221, v222
	v_bfe_u32 v222, v44, 8, 1
	v_lshl_add_u32 v221, v222, 2, v221
	v_lshlrev_b32_e32 v221, 4, v221
	v_lshl_add_u32 v220, v220, 10, v221
	v_mov_b32_e32 v221, 0
	v_lshl_add_u64 v[196:197], s[26:27], 0, v[220:221]
	s_lshl_b32 s4, s35, 4
	v_bfe_u32 v2, v44, 2, 4
	v_and_or_b32 v2, s4, 48, v2
	s_ashr_i32 s4, s6, 3
	s_andn2_b32 s4, s4, 31
	v_lshlrev_b32_e32 v2, 10, v2
	s_ashr_i32 s5, s4, 31
	s_lshl_b32 s37, s35, 10
	v_lshl_add_u64 v[4:5], s[28:29], 0, v[2:3]
	v_lshlrev_b32_e32 v205, 3, v44
	s_cmp_lg_u32 16, -1
	v_lshl_add_u64 v[4:5], s[4:5], 1, v[4:5]
	v_and_b32_e32 v45, 24, v205
	s_cselect_b32 s4, 16, 0
	v_bfe_u32 v100, v44, 5, 1
	v_lshlrev_b32_e32 v2, 1, v45
	s_add_i32 s37, s37, s4
	s_mov_b32 s4, m0
	s_mov_b32 m0, s37
	s_nop 0
	global_load_lds_dwordx4 v[196:197], off
	s_mov_b32 m0, s4
	v_and_b32_e32 v206, 31, v44
	v_lshl_add_u64 v[200:201], v[4:5], 0, v[2:3]
	s_add_i32 s38, s37, 0x6000
	s_mov_b32 s4, m0
	s_mov_b32 m0, s38
	s_nop 0
	global_load_lds_dwordx4 v[200:201], off
	s_mov_b32 m0, s4
	v_lshlrev_b32_e32 v192, 4, v100
	v_lshl_add_u64 v[4:5], v[196:197], 0, s[10:11]
	s_add_i32 s4, s37, 0x2000
	s_mov_b32 s5, m0
	s_mov_b32 m0, s4
	s_nop 0
	global_load_lds_dwordx4 v[4:5], off
	s_mov_b32 m0, s5
	v_lshl_or_b32 v2, v206, 10, v192
	global_load_dwordx4 v[128:131], v2, s[0:1]
	global_load_dwordx4 v[124:127], v2, s[0:1] offset:32
	global_load_dwordx4 v[116:119], v2, s[0:1] offset:64
	global_load_dwordx4 v[108:111], v2, s[0:1] offset:96
	v_lshlrev_b32_e32 v2, 10, v100
	v_lshlrev_b32_e32 v4, 4, v206
	v_add3_u32 v211, 16, v2, v4
	v_bfe_u32 v222, v206, 2, 2
	v_and_b32_e32 v223, 1, v222
	v_xor_b32_e32 v223, v223, v100
	v_and_b32_e32 v222, 2, v222
	v_or_b32_e32 v222, v222, v223
	v_lshlrev_b32_e32 v222, 4, v222
	v_lshl_add_u32 v211, v206, 6, v222
	v_xor_b32_e32 v225, 32, v211
	v_add_u32_e32 v211, 16, v211
	v_add_u32_e32 v225, 16, v225
	v_lshl_add_u64 v[4:5], v[196:197], 0, s[12:13]
	s_add_i32 s0, s37, 0x4000
	s_mov_b32 s1, m0
	s_mov_b32 m0, s0
	s_nop 0
	global_load_lds_dwordx4 v[4:5], off
	s_mov_b32 m0, s1
	s_waitcnt vmcnt(3) lgkmcnt(0)
	s_barrier
	ds_read_b128 v[20:23], v211
	v_add_u32_e32 v2, 16, v192
	v_add_u32_e32 v32, 0x14800, v2
	ds_read_b128 v[4:7], v32
	ds_read_b128 v[8:11], v32 offset:32
	ds_read_b128 v[12:15], v32 offset:64
	ds_read_b128 v[16:19], v32 offset:96
	ds_read_b128 v[36:39], v211 offset:2048
	s_waitcnt vmcnt(3) lgkmcnt(1)
	v_mfma_f32_32x32x16_bf16 v[4:19], v[20:23], v[128:131], v[4:19]
	ds_read_b128 v[20:23], v32 offset:128
	ds_read_b128 v[24:27], v32 offset:160
	ds_read_b128 v[28:31], v32 offset:192
	ds_read_b128 v[32:35], v32 offset:224
	v_add_u32_e32 v2, 0x14900, v2
	s_lshl_b32 s5, s69, 8
	s_addk_i32 s5, 0xe1c0
	v_lshlrev_b32_e32 v208, 2, v100
	s_mov_b32 s4, 0
	s_mov_b32 s6, 5
	s_waitcnt lgkmcnt(0)
	v_mfma_f32_32x32x16_bf16 v[20:35], v[36:39], v[128:131], v[20:35]
	ds_read_b128 v[36:39], v225
	ds_read_b128 v[40:43], v225 offset:2048
	s_movk_i32 s27, 0x2000
	s_add_i32 s26, s36, -5
	v_lshl_add_u32 v207, v206, 2, s30
	v_add_u32_e32 v193, s65, v192
	v_lshl_add_u64 v[188:189], v[200:201], 0, s[14:15]
	v_lshl_add_u64 v[190:191], v[196:197], 0, s[16:17]
	s_waitcnt vmcnt(2) lgkmcnt(1)
	v_mfma_f32_32x32x16_bf16 v[4:19], v[36:39], v[124:127], v[4:19]
	v_lshl_add_u64 v[202:203], v[200:201], 0, s[20:21]
	s_waitcnt lgkmcnt(0)
	v_mfma_f32_32x32x16_bf16 v[20:35], v[40:43], v[124:127], v[20:35]
	ds_read_b128 v[36:39], v211 offset:4096
	ds_read_b128 v[40:43], v211 offset:6144
	s_waitcnt vmcnt(1) lgkmcnt(1)
	v_mfma_f32_32x32x16_bf16 v[4:19], v[36:39], v[116:119], v[4:19]
	ds_read_b128 v[36:39], v225 offset:4096
	s_waitcnt lgkmcnt(1)
	v_mfma_f32_32x32x16_bf16 v[20:35], v[40:43], v[116:119], v[20:35]
	v_lshlrev_b32_e32 v40, 1, v44
	v_and_b32_e32 v46, 32, v40
	ds_read_b128 v[40:43], v225 offset:6144
	s_waitcnt vmcnt(0) lgkmcnt(0)
	s_barrier
	s_waitcnt vmcnt(0) lgkmcnt(1)
	v_mfma_f32_32x32x16_bf16 v[4:19], v[36:39], v[108:111], v[4:19]
	v_lshlrev_b32_e32 v38, 4, v44
	v_add3_u32 v36, 16, v46, v45
	v_lshlrev_b32_e32 v37, 8, v100
	v_and_b32_e32 v38, 0xc0, v38
	v_add3_u32 v209, v36, v37, v38
	s_nop 6
	v_max_f32_e32 v36, v5, v5
	s_waitcnt lgkmcnt(0)
	v_mfma_f32_32x32x16_bf16 v[20:35], v[40:43], v[108:111], v[20:35]
	v_max_f32_e32 v37, v4, v4
	v_max_f32_e32 v36, v37, v36
	s_nop 9
	v_max3_f32 v37, v6, v7, v21
	v_max3_f32 v36, v36, v20, v22
	v_max3_f32 v36, v36, v23, v8
	v_max3_f32 v37, v37, v10, v11
	v_max3_f32 v36, v36, v9, v24
	v_max3_f32 v37, v37, v26, v27
	v_max3_f32 v36, v36, v25, v12
	v_max3_f32 v37, v37, v14, v15
	v_max3_f32 v36, v36, v13, v28
	v_max3_f32 v37, v37, v30, v31
	v_max3_f32 v36, v36, v29, v16
	v_max3_f32 v37, v37, v18, v19
	v_max3_f32 v36, v36, v17, v32
	v_max3_f32 v37, v37, v34, v35
	v_max3_f32 v68, v36, v33, v37
	v_lshl_add_u64 v[36:37], v[196:197], 0, s[14:15]
	s_mov_b32 s0, m0
	s_mov_b32 m0, s37
	s_nop 0
	global_load_lds_dwordx4 v[36:37], off
	s_mov_b32 m0, s0
	v_mov_b32_e32 v69, v68
	v_lshl_add_u64 v[36:37], v[200:201], 0, s[10:11]
	s_add_i32 s0, s37, 0x8000
	s_mov_b32 s1, m0
	s_mov_b32 m0, s0
	s_nop 0
	global_load_lds_dwordx4 v[36:37], off
	s_mov_b32 m0, s1
	v_permlane32_swap_b32_e32 v68, v69
	ds_read_b128 v[160:163], v211 offset:8192
	ds_read_b128 v[156:159], v211 offset:10240
	ds_read_b128 v[152:155], v225 offset:8192
	ds_read_b128 v[148:151], v225 offset:10240
	ds_read_b128 v[144:147], v211 offset:12288
	ds_read_b128 v[140:143], v211 offset:14336
	ds_read_b128 v[136:139], v225 offset:12288
	ds_read_b128 v[132:135], v225 offset:14336
	s_waitcnt vmcnt(2) lgkmcnt(0)
	s_barrier
	ds_read_b128 v[36:39], v2 offset:128
	ds_read_b128 v[40:43], v2 offset:160
	ds_read_b128 v[44:47], v2 offset:192
	ds_read_b128 v[48:51], v2 offset:224
	ds_read_b128 v[52:55], v2
	ds_read_b128 v[56:59], v2 offset:32
	ds_read_b128 v[60:63], v2 offset:64
	ds_read_b128 v[64:67], v2 offset:96
	v_max_f32_e32 v2, v69, v69
	v_max_f32_e32 v68, v68, v68
	v_max_f32_e32 v210, v68, v2
	v_sub_f32_e32 v2, v20, v210
	v_exp_f32_e32 v68, v2
	v_sub_f32_e32 v2, v21, v210
	v_exp_f32_e32 v69, v2
	v_sub_f32_e32 v2, v22, v210
	v_exp_f32_e32 v70, v2
	v_sub_f32_e32 v2, v23, v210
	v_exp_f32_e32 v71, v2
	v_sub_f32_e32 v2, v24, v210
	v_exp_f32_e32 v72, v2
	v_sub_f32_e32 v2, v25, v210
	v_exp_f32_e32 v73, v2
	v_sub_f32_e32 v2, v26, v210
	v_exp_f32_e32 v74, v2
	v_sub_f32_e32 v2, v27, v210
	v_exp_f32_e32 v75, v2
	v_sub_f32_e32 v2, v28, v210
	v_exp_f32_e32 v76, v2
	v_sub_f32_e32 v2, v29, v210
	v_exp_f32_e32 v77, v2
	v_sub_f32_e32 v2, v30, v210
	v_exp_f32_e32 v78, v2
	v_sub_f32_e32 v2, v31, v210
	v_exp_f32_e32 v79, v2
	v_sub_f32_e32 v2, v32, v210
	v_exp_f32_e32 v80, v2
	v_sub_f32_e32 v2, v33, v210
	v_exp_f32_e32 v81, v2
	v_sub_f32_e32 v2, v34, v210
	v_exp_f32_e32 v82, v2
	v_sub_f32_e32 v2, v35, v210
	v_exp_f32_e32 v83, v2
	v_sub_f32_e32 v2, v4, v210
	v_exp_f32_e32 v84, v2
	v_sub_f32_e32 v2, v5, v210
	v_exp_f32_e32 v85, v2
	v_sub_f32_e32 v2, v6, v210
	v_exp_f32_e32 v86, v2
	v_sub_f32_e32 v2, v7, v210
	v_exp_f32_e32 v87, v2
	v_sub_f32_e32 v2, v8, v210
	v_exp_f32_e32 v88, v2
	v_sub_f32_e32 v2, v9, v210
	v_exp_f32_e32 v89, v2
	v_sub_f32_e32 v2, v10, v210
	v_exp_f32_e32 v90, v2
	v_sub_f32_e32 v2, v11, v210
	v_exp_f32_e32 v91, v2
	v_sub_f32_e32 v2, v12, v210
	v_exp_f32_e32 v92, v2
	v_sub_f32_e32 v2, v13, v210
	v_exp_f32_e32 v93, v2
	v_sub_f32_e32 v2, v14, v210
	v_exp_f32_e32 v94, v2
	v_sub_f32_e32 v2, v15, v210
	v_exp_f32_e32 v95, v2
	v_sub_f32_e32 v2, v16, v210
	v_exp_f32_e32 v96, v2
	v_sub_f32_e32 v2, v17, v210
	v_exp_f32_e32 v97, v2
	v_sub_f32_e32 v2, v18, v210
	v_exp_f32_e32 v98, v2
	v_sub_f32_e32 v2, v19, v210
	v_exp_f32_e32 v99, v2
	v_or_b32_e32 v2, s5, v208
	s_lshl_b32 s5, s22, 12
	v_mov_b32_e32 v16, v3
	v_mov_b32_e32 v17, v3
	v_subrev_u32_e32 v212, s5, v2
	v_mov_b32_e32 v2, v3
	v_mov_b32_e32 v4, v3
	v_mov_b32_e32 v5, v3
	v_mov_b32_e32 v6, v3
	v_mov_b32_e32 v7, v3
	v_mov_b32_e32 v8, v3
	v_mov_b32_e32 v9, v3
	v_mov_b32_e32 v10, v3
	v_mov_b32_e32 v11, v3
	v_mov_b32_e32 v12, v3
	v_mov_b32_e32 v13, v3
	v_mov_b32_e32 v14, v3
	v_mov_b32_e32 v15, v3
	v_mov_b64_e32 v[34:35], v[16:17]
	s_add_i32 s5, 16, 0x14c00
	v_mov_b64_e32 v[32:33], v[14:15]
	v_mov_b64_e32 v[30:31], v[12:13]
	v_mov_b64_e32 v[28:29], v[10:11]
	v_mov_b64_e32 v[26:27], v[8:9]
	v_mov_b64_e32 v[24:25], v[6:7]
	v_mov_b64_e32 v[22:23], v[4:5]
	v_mov_b64_e32 v[20:21], v[2:3]
	v_mov_b64_e32 v[18:19], v[16:17]
	v_cmp_gt_u32_e64 s[0:1], 32, v204
	v_add_u32_e32 v213, s5, v192
	v_mov_b64_e32 v[16:17], v[14:15]
	v_mov_b64_e32 v[14:15], v[12:13]
	v_mov_b64_e32 v[12:13], v[10:11]
	v_mov_b64_e32 v[10:11], v[8:9]
	v_mov_b64_e32 v[8:9], v[6:7]
	v_mov_b64_e32 v[6:7], v[4:5]
	v_mov_b64_e32 v[4:5], v[2:3]

.LBB0_2054:
	s_setprio 0
	s_waitcnt vmcnt(0)
	s_barrier
	s_mov_b64 s[0:1], exec
	v_readlane_b32 s4, v254, 0
	v_readlane_b32 s5, v254, 1
	s_and_b64 s[4:5], s[0:1], s[4:5]
	v_readlane_b32 s96, v254, 20
	s_mov_b64 exec, s[4:5]
	s_cbranch_execz .LBB0_2106
	v_mov_b32_e32 v18, 0
	s_waitcnt vmcnt(0) expcnt(0) lgkmcnt(0)
	ds_read_b32 v4, v18
	ds_read_b32 v2, v18 offset:4
	s_waitcnt lgkmcnt(1)
	v_cmp_ne_u32_e32 vcc, 0, v4
	s_cbranch_vccnz .LBB0_2070
	v_readlane_b32 s2, v254, 45
	v_readlane_b32 s3, v254, 46
	s_load_dwordx2 s[8:9], s[2:3], 0x4
	s_add_u32 s4, s90, 0x1e26c00
	s_addc_u32 s5, s91, 0
	s_add_u32 s6, s90, 0x1e26e00
	s_addc_u32 s7, s91, 0
	s_waitcnt lgkmcnt(0)
	s_mul_i32 s64, s8, s33
	s_add_u32 s8, s90, 0x1e26f00
	s_mul_i32 s64, s64, s9
	s_addc_u32 s9, s91, 0
	s_add_u32 s10, s90, 0x1e27000
	s_addc_u32 s11, s91, 0
	s_add_u32 s12, s90, 0x1e27100
	s_addc_u32 s13, s91, 0
	s_add_u32 s14, s90, 0x1e27200
	s_addc_u32 s15, s91, 0
	s_add_u32 s16, s90, 0x1e27300
	s_addc_u32 s17, s91, 0
	s_add_u32 s18, s90, 0x1e27400
	s_addc_u32 s19, s91, 0
	s_add_u32 s20, s90, 0x1e27500
	s_addc_u32 s21, s91, 0
	s_add_u32 s22, s90, 0x1e27600
	s_addc_u32 s23, s91, 0
	s_add_u32 s24, s90, 0x1e27700
	s_addc_u32 s25, s91, 0
	s_add_u32 s26, s90, 0x1e27800
	s_addc_u32 s27, s91, 0
	s_add_u32 s28, s90, 0x1e27900
	s_addc_u32 s29, s91, 0
	s_add_u32 s30, s90, 0x1e27a00
	s_addc_u32 s31, s91, 0
	s_add_u32 s34, s90, 0x1e27b00
	s_addc_u32 s35, s91, 0
	s_add_u32 s36, s90, 0x1e27c00
	s_addc_u32 s37, s91, 0
	s_add_u32 s38, s90, 0x1e27d00
	s_addc_u32 s39, s91, 0
	s_mov_b32 s65, 1
	s_branch .LBB0_2058
